# EpiDil rope epilogue de-serialised: cos/sin loads for 4 row groups in flight with counted vmcnt (was 8 serial round trips per tile), on top of P0 and P3 changes
# speedup vs baseline: 1.0116x; 1.0116x over previous
;     __device__ __forceinline__ void operator()(const f32x4 (&acc)[2][2][4][2], const pg8::Unit& u, int wr, int wc, int fr, int fq) const {
;     ...
;         } else {
;             const float sc = seg == 0 ? 0.08838834764831845f : 1.0f;
;             const int g4 = 4 * (4 * wc + fq);
; #pragma unroll
;             for (int ai = 0; ai < 2; ++ai)
; #pragma unroll
;                 for (int m = 0; m < 4; ++m) {
;                     const int row = row0 + ai * 128 + m * 16;
;                     const f32x4 c4 = *(const f32x4*)(cosT + (size_t)row * 64 + g4) * sc, s4 = *(const f32x4*)(sinT + (size_t)row * 64 + g4) * sc;
;                     bf16_t* rowp = base + (size_t)row * 3072 + col0;
; #pragma unroll
;                     for (int bj = 0; bj < 2; ++bj) {
;                         const f32x4 x1 = acc[ai][bj][m][0], x2 = acc[ai][bj][m][1];
;                         store8(rowp + bj * 128, x1 * c4 - x2 * s4, x2 * c4 + x1 * s4);
;                     }
;                     asm volatile("" ::: "memory");
.LBB0_439:
	v_ashrrev_i32_e32 v181, 31, v180
	v_ashrrev_i32_e32 v179, 31, v178
	v_ashrrev_i32_e32 v177, 31, v176
	v_ashrrev_i32_e32 v175, 31, v174
	v_ashrrev_i32_e32 v173, 31, v172
	v_ashrrev_i32_e32 v171, 31, v170
	v_ashrrev_i32_e32 v169, 31, v168
	v_ashrrev_i32_e32 v167, 31, v166
	s_add_i32 s6, s96, 11
	s_cmp_lt_u32 s6, 23
	s_cselect_b64 vcc, -1, 0
	v_cndmask_b32_e32 v186, 1.0, v155, vcc
	v_lshl_add_u64 v[184:185], v[182:183], 1, s[64:65]
	v_lshlrev_b64 v[202:203], 8, v[180:181]
	v_lshl_add_u64 v[204:205], v[148:149], 0, v[202:203]
	global_load_dwordx4 v[220:223], v[204:205], off
	v_lshl_add_u64 v[204:205], v[150:151], 0, v[202:203]
	global_load_dwordx4 v[224:227], v[204:205], off
	v_lshlrev_b64 v[202:203], 8, v[178:179]
	v_lshl_add_u64 v[204:205], v[148:149], 0, v[202:203]
	global_load_dwordx4 v[228:231], v[204:205], off
	v_lshl_add_u64 v[204:205], v[150:151], 0, v[202:203]
	global_load_dwordx4 v[232:235], v[204:205], off
	v_lshlrev_b64 v[202:203], 8, v[176:177]
	v_lshl_add_u64 v[204:205], v[148:149], 0, v[202:203]
	global_load_dwordx4 v[236:239], v[204:205], off
	v_lshl_add_u64 v[204:205], v[150:151], 0, v[202:203]
	global_load_dwordx4 v[240:243], v[204:205], off
	v_lshlrev_b64 v[202:203], 8, v[174:175]
	v_lshl_add_u64 v[204:205], v[148:149], 0, v[202:203]
	global_load_dwordx4 v[244:247], v[204:205], off
	v_lshl_add_u64 v[204:205], v[150:151], 0, v[202:203]
	global_load_dwordx4 v[248:251], v[204:205], off
	v_mad_i64_i32 v[200:201], s[6:7], v180, s75, v[184:185]
	s_waitcnt vmcnt(6)
	v_pk_mul_f32 v[192:193], v[186:187], v[220:221] op_sel_hi:[0,1]
	v_pk_mul_f32 v[194:195], v[186:187], v[222:223] op_sel_hi:[0,1]
	v_pk_mul_f32 v[198:199], v[186:187], v[226:227] op_sel_hi:[0,1]
	v_pk_mul_f32 v[196:197], v[186:187], v[224:225] op_sel_hi:[0,1]
	v_pk_mul_f32 v[206:207], v[120:121], v[196:197]
	v_pk_mul_f32 v[208:209], v[122:123], v[198:199]
	v_pk_mul_f32 v[210:211], v[124:125], v[196:197]
	v_pk_mul_f32 v[212:213], v[126:127], v[198:199]
	v_pk_mul_f32 v[214:215], v[104:105], v[196:197]
	v_pk_mul_f32 v[216:217], v[106:107], v[198:199]
	v_pk_mul_f32 v[196:197], v[108:109], v[196:197]
	v_pk_mul_f32 v[198:199], v[110:111], v[198:199]
	v_pk_fma_f32 v[208:209], v[126:127], v[194:195], v[208:209] neg_lo:[0,0,1] neg_hi:[0,0,1]
	v_pk_fma_f32 v[206:207], v[124:125], v[192:193], v[206:207] neg_lo:[0,0,1] neg_hi:[0,0,1]
	v_pk_fma_f32 v[212:213], v[122:123], v[194:195], v[212:213]
	v_pk_fma_f32 v[210:211], v[120:121], v[192:193], v[210:211]
	v_pk_fma_f32 v[216:217], v[110:111], v[194:195], v[216:217] neg_lo:[0,0,1] neg_hi:[0,0,1]
	v_pk_fma_f32 v[214:215], v[108:109], v[192:193], v[214:215] neg_lo:[0,0,1] neg_hi:[0,0,1]
	v_pk_fma_f32 v[218:219], v[106:107], v[194:195], v[198:199]
	v_pk_fma_f32 v[198:199], v[104:105], v[192:193], v[196:197]
	v_cvt_pk_bf16_f32 v192, v206, v207
	v_cvt_pk_bf16_f32 v193, v208, v209
	v_cvt_pk_bf16_f32 v194, v210, v211
	v_cvt_pk_bf16_f32 v195, v212, v213
	v_cvt_pk_bf16_f32 v196, v214, v215
	v_cvt_pk_bf16_f32 v197, v216, v217
	v_cvt_pk_bf16_f32 v198, v198, v199
	v_cvt_pk_bf16_f32 v199, v218, v219
	global_store_dwordx4 v[200:201], v[192:195], off
	global_store_dwordx4 v[200:201], v[196:199], off offset:256
	v_lshlrev_b64 v[202:203], 8, v[172:173]
	v_lshl_add_u64 v[204:205], v[148:149], 0, v[202:203]
	global_load_dwordx4 v[220:223], v[204:205], off
	v_lshl_add_u64 v[204:205], v[150:151], 0, v[202:203]
	global_load_dwordx4 v[224:227], v[204:205], off
	v_mad_i64_i32 v[200:201], s[6:7], v178, s75, v[184:185]
	s_waitcnt vmcnt(8)
	v_pk_mul_f32 v[194:195], v[186:187], v[230:231] op_sel_hi:[0,1]
	v_pk_mul_f32 v[192:193], v[186:187], v[228:229] op_sel_hi:[0,1]
	v_pk_mul_f32 v[198:199], v[186:187], v[234:235] op_sel_hi:[0,1]
	v_pk_mul_f32 v[196:197], v[186:187], v[232:233] op_sel_hi:[0,1]
	v_pk_mul_f32 v[206:207], v[114:115], v[198:199]
	v_pk_mul_f32 v[208:209], v[112:113], v[196:197]
	v_pk_mul_f32 v[210:211], v[118:119], v[198:199]
	v_pk_mul_f32 v[212:213], v[116:117], v[196:197]
	v_pk_mul_f32 v[214:215], v[90:91], v[198:199]
	v_pk_mul_f32 v[216:217], v[88:89], v[196:197]
	v_pk_mul_f32 v[198:199], v[94:95], v[198:199]
	v_pk_mul_f32 v[196:197], v[92:93], v[196:197]
	v_pk_fma_f32 v[206:207], v[118:119], v[194:195], v[206:207] neg_lo:[0,0,1] neg_hi:[0,0,1]
	v_pk_fma_f32 v[208:209], v[116:117], v[192:193], v[208:209] neg_lo:[0,0,1] neg_hi:[0,0,1]
	v_pk_fma_f32 v[210:211], v[114:115], v[194:195], v[210:211]
	v_pk_fma_f32 v[212:213], v[112:113], v[192:193], v[212:213]
	v_pk_fma_f32 v[214:215], v[94:95], v[194:195], v[214:215] neg_lo:[0,0,1] neg_hi:[0,0,1]
	v_pk_fma_f32 v[216:217], v[92:93], v[192:193], v[216:217] neg_lo:[0,0,1] neg_hi:[0,0,1]
	v_pk_fma_f32 v[218:219], v[90:91], v[194:195], v[198:199]
	v_pk_fma_f32 v[198:199], v[88:89], v[192:193], v[196:197]
	v_cvt_pk_bf16_f32 v192, v208, v209
	v_cvt_pk_bf16_f32 v193, v206, v207
	v_cvt_pk_bf16_f32 v194, v212, v213
	v_cvt_pk_bf16_f32 v195, v210, v211
	v_cvt_pk_bf16_f32 v196, v216, v217
	v_cvt_pk_bf16_f32 v197, v214, v215
	v_cvt_pk_bf16_f32 v198, v198, v199
	v_cvt_pk_bf16_f32 v199, v218, v219
	global_store_dwordx4 v[200:201], v[192:195], off
	global_store_dwordx4 v[200:201], v[196:199], off offset:256
	v_lshlrev_b64 v[202:203], 8, v[170:171]
	v_lshl_add_u64 v[204:205], v[148:149], 0, v[202:203]
	global_load_dwordx4 v[228:231], v[204:205], off
	v_lshl_add_u64 v[204:205], v[150:151], 0, v[202:203]
	global_load_dwordx4 v[232:235], v[204:205], off
	v_mad_i64_i32 v[200:201], s[6:7], v176, s75, v[184:185]
	s_waitcnt vmcnt(10)
;     __device__ __forceinline__ void operator()(const f32x4 (&acc)[2][2][4][2], const pg8::Unit& u, int wr, int wc, int fr, int fq) const {
;     ...
;             for (int ai = 0; ai < 2; ++ai)
; #pragma unroll
;                 for (int m = 0; m < 4; ++m) {
;                     const int row = row0 + ai * 128 + m * 16;
;                     const f32x4 c4 = *(const f32x4*)(cosT + (size_t)row * 64 + g4) * sc, s4 = *(const f32x4*)(sinT + (size_t)row * 64 + g4) * sc;
;                     bf16_t* rowp = base + (size_t)row * 3072 + col0;
; #pragma unroll
;                     for (int bj = 0; bj < 2; ++bj) {
;                         const f32x4 x1 = acc[ai][bj][m][0], x2 = acc[ai][bj][m][1];
;                         store8(rowp + bj * 128, x1 * c4 - x2 * s4, x2 * c4 + x1 * s4);
;                     }
;                     asm volatile("" ::: "memory");
	v_pk_mul_f32 v[194:195], v[186:187], v[238:239] op_sel_hi:[0,1]
	v_pk_mul_f32 v[192:193], v[186:187], v[236:237] op_sel_hi:[0,1]
	v_pk_mul_f32 v[198:199], v[186:187], v[242:243] op_sel_hi:[0,1]
	v_pk_mul_f32 v[196:197], v[186:187], v[240:241] op_sel_hi:[0,1]
	v_pk_mul_f32 v[206:207], v[98:99], v[198:199]
	v_pk_mul_f32 v[208:209], v[96:97], v[196:197]
	v_pk_mul_f32 v[210:211], v[102:103], v[198:199]
	v_pk_mul_f32 v[212:213], v[100:101], v[196:197]
	v_pk_mul_f32 v[214:215], v[74:75], v[198:199]
	v_pk_mul_f32 v[216:217], v[72:73], v[196:197]
	v_pk_mul_f32 v[198:199], v[78:79], v[198:199]
	v_pk_mul_f32 v[196:197], v[76:77], v[196:197]
	v_pk_fma_f32 v[206:207], v[102:103], v[194:195], v[206:207] neg_lo:[0,0,1] neg_hi:[0,0,1]
	v_pk_fma_f32 v[208:209], v[100:101], v[192:193], v[208:209] neg_lo:[0,0,1] neg_hi:[0,0,1]
	v_pk_fma_f32 v[210:211], v[98:99], v[194:195], v[210:211]
	v_pk_fma_f32 v[212:213], v[96:97], v[192:193], v[212:213]
	v_pk_fma_f32 v[214:215], v[78:79], v[194:195], v[214:215] neg_lo:[0,0,1] neg_hi:[0,0,1]
	v_pk_fma_f32 v[216:217], v[76:77], v[192:193], v[216:217] neg_lo:[0,0,1] neg_hi:[0,0,1]
	v_pk_fma_f32 v[218:219], v[74:75], v[194:195], v[198:199]
	v_pk_fma_f32 v[198:199], v[72:73], v[192:193], v[196:197]
	v_cvt_pk_bf16_f32 v192, v208, v209
	v_cvt_pk_bf16_f32 v193, v206, v207
	v_cvt_pk_bf16_f32 v194, v212, v213
	v_cvt_pk_bf16_f32 v195, v210, v211
	v_cvt_pk_bf16_f32 v196, v216, v217
	v_cvt_pk_bf16_f32 v197, v214, v215
	v_cvt_pk_bf16_f32 v198, v198, v199
	v_cvt_pk_bf16_f32 v199, v218, v219
	global_store_dwordx4 v[200:201], v[192:195], off
	global_store_dwordx4 v[200:201], v[196:199], off offset:256
	v_lshlrev_b64 v[202:203], 8, v[168:169]
	v_lshl_add_u64 v[204:205], v[148:149], 0, v[202:203]
	global_load_dwordx4 v[236:239], v[204:205], off
	v_lshl_add_u64 v[204:205], v[150:151], 0, v[202:203]
	global_load_dwordx4 v[240:243], v[204:205], off
	v_mad_i64_i32 v[200:201], s[6:7], v174, s75, v[184:185]
	s_waitcnt vmcnt(12)
	v_pk_mul_f32 v[194:195], v[186:187], v[246:247] op_sel_hi:[0,1]
	v_pk_mul_f32 v[192:193], v[186:187], v[244:245] op_sel_hi:[0,1]
	v_pk_mul_f32 v[198:199], v[186:187], v[250:251] op_sel_hi:[0,1]
	v_pk_mul_f32 v[196:197], v[186:187], v[248:249] op_sel_hi:[0,1]
	v_pk_mul_f32 v[206:207], v[82:83], v[198:199]
	v_pk_mul_f32 v[208:209], v[80:81], v[196:197]
	v_pk_mul_f32 v[210:211], v[86:87], v[198:199]
	v_pk_mul_f32 v[212:213], v[84:85], v[196:197]
	v_pk_mul_f32 v[214:215], v[66:67], v[198:199]
	v_pk_mul_f32 v[216:217], v[64:65], v[196:197]
	v_pk_mul_f32 v[198:199], v[70:71], v[198:199]
	v_pk_mul_f32 v[196:197], v[68:69], v[196:197]
	v_pk_fma_f32 v[206:207], v[86:87], v[194:195], v[206:207] neg_lo:[0,0,1] neg_hi:[0,0,1]
	v_pk_fma_f32 v[208:209], v[84:85], v[192:193], v[208:209] neg_lo:[0,0,1] neg_hi:[0,0,1]
	v_pk_fma_f32 v[210:211], v[82:83], v[194:195], v[210:211]
	v_pk_fma_f32 v[212:213], v[80:81], v[192:193], v[212:213]
	v_pk_fma_f32 v[214:215], v[70:71], v[194:195], v[214:215] neg_lo:[0,0,1] neg_hi:[0,0,1]
	v_pk_fma_f32 v[216:217], v[68:69], v[192:193], v[216:217] neg_lo:[0,0,1] neg_hi:[0,0,1]
	v_pk_fma_f32 v[218:219], v[66:67], v[194:195], v[198:199]
	v_pk_fma_f32 v[198:199], v[64:65], v[192:193], v[196:197]
	v_cvt_pk_bf16_f32 v192, v208, v209
	v_cvt_pk_bf16_f32 v193, v206, v207
	v_cvt_pk_bf16_f32 v194, v212, v213
	v_cvt_pk_bf16_f32 v195, v210, v211
	v_cvt_pk_bf16_f32 v196, v216, v217
	v_cvt_pk_bf16_f32 v197, v214, v215
	v_cvt_pk_bf16_f32 v198, v198, v199
	v_cvt_pk_bf16_f32 v199, v218, v219
	global_store_dwordx4 v[200:201], v[192:195], off
	global_store_dwordx4 v[200:201], v[196:199], off offset:256
	v_lshlrev_b64 v[202:203], 8, v[166:167]
	v_lshl_add_u64 v[204:205], v[148:149], 0, v[202:203]
	global_load_dwordx4 v[244:247], v[204:205], off
	v_lshl_add_u64 v[204:205], v[150:151], 0, v[202:203]
	global_load_dwordx4 v[248:251], v[204:205], off
	v_mad_i64_i32 v[200:201], s[6:7], v172, s75, v[184:185]
	s_waitcnt vmcnt(12)
	v_pk_mul_f32 v[194:195], v[186:187], v[222:223] op_sel_hi:[0,1]
	v_pk_mul_f32 v[192:193], v[186:187], v[220:221] op_sel_hi:[0,1]
	v_pk_mul_f32 v[198:199], v[186:187], v[226:227] op_sel_hi:[0,1]
	v_pk_mul_f32 v[196:197], v[186:187], v[224:225] op_sel_hi:[0,1]
	v_pk_mul_f32 v[206:207], v[58:59], v[198:199]
	v_pk_mul_f32 v[208:209], v[56:57], v[196:197]
	v_pk_mul_f32 v[210:211], v[62:63], v[198:199]
	v_pk_mul_f32 v[212:213], v[60:61], v[196:197]
	v_pk_mul_f32 v[214:215], v[42:43], v[198:199]
	v_pk_mul_f32 v[216:217], v[40:41], v[196:197]
	v_pk_mul_f32 v[198:199], v[46:47], v[198:199]
	v_pk_mul_f32 v[196:197], v[44:45], v[196:197]
	v_pk_fma_f32 v[206:207], v[62:63], v[194:195], v[206:207] neg_lo:[0,0,1] neg_hi:[0,0,1]
	v_pk_fma_f32 v[208:209], v[60:61], v[192:193], v[208:209] neg_lo:[0,0,1] neg_hi:[0,0,1]
	v_pk_fma_f32 v[210:211], v[58:59], v[194:195], v[210:211]
	v_pk_fma_f32 v[212:213], v[56:57], v[192:193], v[212:213]
	v_pk_fma_f32 v[214:215], v[46:47], v[194:195], v[214:215] neg_lo:[0,0,1] neg_hi:[0,0,1]
	v_pk_fma_f32 v[216:217], v[44:45], v[192:193], v[216:217] neg_lo:[0,0,1] neg_hi:[0,0,1]
	v_pk_fma_f32 v[218:219], v[42:43], v[194:195], v[198:199]
	v_pk_fma_f32 v[198:199], v[40:41], v[192:193], v[196:197]
	v_cvt_pk_bf16_f32 v192, v208, v209
	v_cvt_pk_bf16_f32 v193, v206, v207
	v_cvt_pk_bf16_f32 v194, v212, v213
	v_cvt_pk_bf16_f32 v195, v210, v211
	v_cvt_pk_bf16_f32 v196, v216, v217
	v_cvt_pk_bf16_f32 v197, v214, v215
	v_cvt_pk_bf16_f32 v198, v198, v199
	v_cvt_pk_bf16_f32 v199, v218, v219
	global_store_dwordx4 v[200:201], v[192:195], off
	global_store_dwordx4 v[200:201], v[196:199], off offset:256
	v_mad_i64_i32 v[200:201], s[6:7], v170, s75, v[184:185]
	s_waitcnt vmcnt(10)
;     __device__ __forceinline__ void operator()(const f32x4 (&acc)[2][2][4][2], const pg8::Unit& u, int wr, int wc, int fr, int fq) const {
;     ...
;             for (int ai = 0; ai < 2; ++ai)
; #pragma unroll
;                 for (int m = 0; m < 4; ++m) {
;                     const int row = row0 + ai * 128 + m * 16;
;                     const f32x4 c4 = *(const f32x4*)(cosT + (size_t)row * 64 + g4) * sc, s4 = *(const f32x4*)(sinT + (size_t)row * 64 + g4) * sc;
;                     bf16_t* rowp = base + (size_t)row * 3072 + col0;
; #pragma unroll
;                     for (int bj = 0; bj < 2; ++bj) {
;                         const f32x4 x1 = acc[ai][bj][m][0], x2 = acc[ai][bj][m][1];
;                         store8(rowp + bj * 128, x1 * c4 - x2 * s4, x2 * c4 + x1 * s4);
;                     }
;                     asm volatile("" ::: "memory");
;                 }
	v_pk_mul_f32 v[194:195], v[186:187], v[230:231] op_sel_hi:[0,1]
	v_pk_mul_f32 v[192:193], v[186:187], v[228:229] op_sel_hi:[0,1]
	v_pk_mul_f32 v[198:199], v[186:187], v[234:235] op_sel_hi:[0,1]
	v_pk_mul_f32 v[196:197], v[186:187], v[232:233] op_sel_hi:[0,1]
	v_pk_mul_f32 v[206:207], v[50:51], v[198:199]
	v_pk_mul_f32 v[208:209], v[48:49], v[196:197]
	v_pk_mul_f32 v[210:211], v[54:55], v[198:199]
	v_pk_mul_f32 v[212:213], v[52:53], v[196:197]
	v_pk_mul_f32 v[214:215], v[26:27], v[198:199]
	v_pk_mul_f32 v[216:217], v[24:25], v[196:197]
	v_pk_mul_f32 v[198:199], v[30:31], v[198:199]
	v_pk_mul_f32 v[196:197], v[28:29], v[196:197]
	v_pk_fma_f32 v[206:207], v[54:55], v[194:195], v[206:207] neg_lo:[0,0,1] neg_hi:[0,0,1]
	v_pk_fma_f32 v[208:209], v[52:53], v[192:193], v[208:209] neg_lo:[0,0,1] neg_hi:[0,0,1]
	v_pk_fma_f32 v[210:211], v[50:51], v[194:195], v[210:211]
	v_pk_fma_f32 v[212:213], v[48:49], v[192:193], v[212:213]
	v_pk_fma_f32 v[214:215], v[30:31], v[194:195], v[214:215] neg_lo:[0,0,1] neg_hi:[0,0,1]
	v_pk_fma_f32 v[216:217], v[28:29], v[192:193], v[216:217] neg_lo:[0,0,1] neg_hi:[0,0,1]
	v_pk_fma_f32 v[218:219], v[26:27], v[194:195], v[198:199]
	v_pk_fma_f32 v[198:199], v[24:25], v[192:193], v[196:197]
	v_cvt_pk_bf16_f32 v192, v208, v209
	v_cvt_pk_bf16_f32 v193, v206, v207
	v_cvt_pk_bf16_f32 v194, v212, v213
	v_cvt_pk_bf16_f32 v195, v210, v211
	v_cvt_pk_bf16_f32 v196, v216, v217
	v_cvt_pk_bf16_f32 v197, v214, v215
	v_cvt_pk_bf16_f32 v198, v198, v199
	v_cvt_pk_bf16_f32 v199, v218, v219
	global_store_dwordx4 v[200:201], v[192:195], off
	global_store_dwordx4 v[200:201], v[196:199], off offset:256
	v_mad_i64_i32 v[200:201], s[6:7], v168, s75, v[184:185]
	s_waitcnt vmcnt(8)
	v_pk_mul_f32 v[194:195], v[186:187], v[238:239] op_sel_hi:[0,1]
	v_pk_mul_f32 v[192:193], v[186:187], v[236:237] op_sel_hi:[0,1]
	v_pk_mul_f32 v[198:199], v[186:187], v[242:243] op_sel_hi:[0,1]
	v_pk_mul_f32 v[196:197], v[186:187], v[240:241] op_sel_hi:[0,1]
	v_pk_mul_f32 v[206:207], v[34:35], v[198:199]
	v_pk_mul_f32 v[208:209], v[32:33], v[196:197]
	v_pk_mul_f32 v[210:211], v[38:39], v[198:199]
	v_pk_mul_f32 v[212:213], v[36:37], v[196:197]
	v_pk_mul_f32 v[214:215], v[10:11], v[198:199]
	v_pk_mul_f32 v[216:217], v[8:9], v[196:197]
	v_pk_mul_f32 v[198:199], v[14:15], v[198:199]
	v_pk_mul_f32 v[196:197], v[12:13], v[196:197]
	v_pk_fma_f32 v[206:207], v[38:39], v[194:195], v[206:207] neg_lo:[0,0,1] neg_hi:[0,0,1]
	v_pk_fma_f32 v[208:209], v[36:37], v[192:193], v[208:209] neg_lo:[0,0,1] neg_hi:[0,0,1]
	v_pk_fma_f32 v[210:211], v[34:35], v[194:195], v[210:211]
	v_pk_fma_f32 v[212:213], v[32:33], v[192:193], v[212:213]
	v_pk_fma_f32 v[214:215], v[14:15], v[194:195], v[214:215] neg_lo:[0,0,1] neg_hi:[0,0,1]
	v_pk_fma_f32 v[216:217], v[12:13], v[192:193], v[216:217] neg_lo:[0,0,1] neg_hi:[0,0,1]
	v_pk_fma_f32 v[218:219], v[10:11], v[194:195], v[198:199]
	v_pk_fma_f32 v[198:199], v[8:9], v[192:193], v[196:197]
	v_cvt_pk_bf16_f32 v192, v208, v209
	v_cvt_pk_bf16_f32 v193, v206, v207
	v_cvt_pk_bf16_f32 v194, v212, v213
	v_cvt_pk_bf16_f32 v195, v210, v211
	v_cvt_pk_bf16_f32 v196, v216, v217
	v_cvt_pk_bf16_f32 v197, v214, v215
	v_cvt_pk_bf16_f32 v198, v198, v199
	v_cvt_pk_bf16_f32 v199, v218, v219
	global_store_dwordx4 v[200:201], v[192:195], off
	global_store_dwordx4 v[200:201], v[196:199], off offset:256
	v_mad_i64_i32 v[184:185], s[6:7], v166, s75, v[184:185]
	s_waitcnt vmcnt(6)
	v_pk_mul_f32 v[194:195], v[186:187], v[246:247] op_sel_hi:[0,1]
	v_pk_mul_f32 v[192:193], v[186:187], v[244:245] op_sel_hi:[0,1]
	v_pk_mul_f32 v[198:199], v[186:187], v[250:251] op_sel_hi:[0,1]
	v_pk_mul_f32 v[196:197], v[186:187], v[248:249] op_sel_hi:[0,1]
	v_pk_mul_f32 v[200:201], v[18:19], v[198:199]
	v_pk_mul_f32 v[202:203], v[16:17], v[196:197]
	v_pk_mul_f32 v[204:205], v[22:23], v[198:199]
	v_pk_mul_f32 v[206:207], v[20:21], v[196:197]
	v_pk_mul_f32 v[208:209], v[2:3], v[198:199]
	v_pk_mul_f32 v[210:211], v[0:1], v[196:197]
	v_pk_mul_f32 v[198:199], v[6:7], v[198:199]
	v_pk_mul_f32 v[196:197], v[4:5], v[196:197]
	v_pk_fma_f32 v[200:201], v[22:23], v[194:195], v[200:201] neg_lo:[0,0,1] neg_hi:[0,0,1]
	v_pk_fma_f32 v[202:203], v[20:21], v[192:193], v[202:203] neg_lo:[0,0,1] neg_hi:[0,0,1]
	v_pk_fma_f32 v[204:205], v[18:19], v[194:195], v[204:205]
	v_pk_fma_f32 v[206:207], v[16:17], v[192:193], v[206:207]
	v_pk_fma_f32 v[208:209], v[6:7], v[194:195], v[208:209] neg_lo:[0,0,1] neg_hi:[0,0,1]
	v_pk_fma_f32 v[210:211], v[4:5], v[192:193], v[210:211] neg_lo:[0,0,1] neg_hi:[0,0,1]
	v_pk_fma_f32 v[212:213], v[2:3], v[194:195], v[198:199]
	v_pk_fma_f32 v[198:199], v[0:1], v[192:193], v[196:197]
	v_cvt_pk_bf16_f32 v192, v202, v203
	v_cvt_pk_bf16_f32 v193, v200, v201
	v_cvt_pk_bf16_f32 v194, v206, v207
	v_cvt_pk_bf16_f32 v195, v204, v205
	v_cvt_pk_bf16_f32 v196, v210, v211
	v_cvt_pk_bf16_f32 v197, v208, v209
	v_cvt_pk_bf16_f32 v198, v198, v199
	v_cvt_pk_bf16_f32 v199, v212, v213
	global_store_dwordx4 v[184:185], v[192:195], off
	global_store_dwordx4 v[184:185], v[196:199], off offset:256
	s_cbranch_execnz .LBB0_438
